# first K iteration peeled with C=0 MFMAs also in the FFN-down, W_out and W_in loops (no accumulator zeroing)
# speedup vs baseline: 1.0112x; 1.0039x over previous
.LBB0_121:
	s_ashr_i32 s59, s58, 31
	s_lshl_b64 s[18:19], s[58:59], 19
	s_add_u32 s60, s46, s18
	s_addc_u32 s61, s47, s19
	s_and_b64 s[18:19], s[6:7], exec
	s_cselect_b32 s16, s61, s69
	s_cselect_b32 s20, s60, s68
	s_ashr_i32 s31, s30, 31
	s_lshl_b64 s[18:19], s[30:31], 19
	s_add_u32 s62, s71, s18
	s_addc_u32 s63, s72, s19
	s_and_b64 s[18:19], s[6:7], exec
	s_cselect_b32 s31, s63, s39
	s_cselect_b32 s59, s62, s38
	s_add_u32 s65, s68, 0x100
	s_addc_u32 s86, s69, 0
	s_add_u32 s87, s38, 0x100
	s_addc_u32 s88, s39, 0
	s_add_u32 s68, s68, 0x80
	s_addc_u32 s69, s69, 0
	s_mov_b32 s89, -2
	s_cmp_eq_u32 s89, 12
	s_cselect_b32 s42, s20, s65
	s_cselect_b32 s43, s16, s86
	s_cselect_b32 s45, s31, s88
	s_cselect_b32 s44, s59, s87
	s_add_u32 s38, s42, 0x80
	s_addc_u32 s39, s43, 0
	s_add_u32 s74, s44, 0x80
	s_addc_u32 s75, s45, 0
	s_add_i32 s35, 0, 0x10000
	s_mov_b64 s[18:19], s[68:69]
	v_add_u32_e32 v140, s35, v142
	s_add_i32 s49, 0, 0x14000
	ds_read_b128 v[136:139], v140
	ds_read_b128 v[144:147], v140 offset:1024
	ds_read_b128 v[148:151], v140 offset:2048
	ds_read_b128 v[152:155], v140 offset:3072
	v_add_u32_e32 v140, s49, v142
	ds_read_b128 v[156:159], v140
	ds_read_b128 v[160:163], v140 offset:1024
	ds_read_b128 v[164:167], v140 offset:2048
	ds_read_b128 v[168:171], v140 offset:3072
	s_mov_b32 m0, s81
	ds_read_b128 v[172:175], v143
	ds_read_b128 v[176:179], v143 offset:1024
	ds_read_b128 v[180:183], v143 offset:2048
	ds_read_b128 v[184:187], v143 offset:3072
	ds_read_b128 v[188:191], v143 offset:4096
	ds_read_b128 v[192:195], v143 offset:5120
	ds_read_b128 v[196:199], v143 offset:6144
	ds_read_b128 v[200:203], v143 offset:7168
	global_load_lds_dwordx4 v130, s[18:19]
	s_mov_b32 m0, s82
	s_nop 0
	global_load_lds_dwordx4 v132, s[18:19]
	s_add_u32 s18, s18, 0x40000
	s_addc_u32 s19, s19, 0
	s_add_i32 m0, s67, 0xc000
	s_nop 0
	global_load_lds_dwordx4 v130, s[18:19]
	s_add_i32 m0, s67, 0xe000
	s_nop 0
	global_load_lds_dwordx4 v132, s[18:19]
	s_waitcnt vmcnt(8)
	s_waitcnt lgkmcnt(0)
	s_barrier
	s_setprio 1
	s_waitcnt lgkmcnt(0)
	v_mfma_f32_16x16x32_bf16 v[126:129], v[136:139], v[172:175], 0
	v_mfma_f32_16x16x32_bf16 v[122:125], v[148:151], v[172:175], 0
	v_mfma_f32_16x16x32_bf16 v[110:113], v[136:139], v[180:183], 0
	v_mfma_f32_16x16x32_bf16 v[106:109], v[148:151], v[180:183], 0
	v_mfma_f32_16x16x32_bf16 v[92:95], v[136:139], v[188:191], 0
	v_mfma_f32_16x16x32_bf16 v[88:91], v[148:151], v[188:191], 0
	v_mfma_f32_16x16x32_bf16 v[76:79], v[136:139], v[196:199], 0
	v_mfma_f32_16x16x32_bf16 v[72:75], v[148:151], v[196:199], 0
	v_mfma_f32_16x16x32_bf16 v[126:129], v[144:147], v[176:179], v[126:129]
	v_mfma_f32_16x16x32_bf16 v[122:125], v[152:155], v[176:179], v[122:125]
	v_mfma_f32_16x16x32_bf16 v[110:113], v[144:147], v[184:187], v[110:113]
	v_mfma_f32_16x16x32_bf16 v[106:109], v[152:155], v[184:187], v[106:109]
	v_mfma_f32_16x16x32_bf16 v[92:95], v[144:147], v[192:195], v[92:95]
	v_mfma_f32_16x16x32_bf16 v[88:91], v[152:155], v[192:195], v[88:91]
	v_mfma_f32_16x16x32_bf16 v[76:79], v[144:147], v[200:203], v[76:79]
	v_mfma_f32_16x16x32_bf16 v[72:75], v[152:155], v[200:203], v[72:75]
	v_mfma_f32_16x16x32_bf16 v[118:121], v[156:159], v[172:175], 0
	v_mfma_f32_16x16x32_bf16 v[114:117], v[164:167], v[172:175], 0
	v_mfma_f32_16x16x32_bf16 v[102:105], v[156:159], v[180:183], 0
	v_mfma_f32_16x16x32_bf16 v[98:101], v[164:167], v[180:183], 0
	v_mfma_f32_16x16x32_bf16 v[84:87], v[156:159], v[188:191], 0
	v_mfma_f32_16x16x32_bf16 v[80:83], v[164:167], v[188:191], 0
	v_mfma_f32_16x16x32_bf16 v[68:71], v[156:159], v[196:199], 0
	v_mfma_f32_16x16x32_bf16 v[64:67], v[164:167], v[196:199], 0
	v_mfma_f32_16x16x32_bf16 v[118:121], v[160:163], v[176:179], v[118:121]
	v_mfma_f32_16x16x32_bf16 v[114:117], v[168:171], v[176:179], v[114:117]
	v_mfma_f32_16x16x32_bf16 v[102:105], v[160:163], v[184:187], v[102:105]
	v_mfma_f32_16x16x32_bf16 v[98:101], v[168:171], v[184:187], v[98:101]
	v_mfma_f32_16x16x32_bf16 v[84:87], v[160:163], v[192:195], v[84:87]
	v_mfma_f32_16x16x32_bf16 v[80:83], v[168:171], v[192:195], v[80:83]
	v_mfma_f32_16x16x32_bf16 v[68:71], v[160:163], v[200:203], v[68:71]
	v_mfma_f32_16x16x32_bf16 v[64:67], v[168:171], v[200:203], v[64:67]
	s_setprio 0
	s_barrier
	s_add_i32 s18, s35, s14
	s_mov_b32 m0, s18
	ds_read_b128 v[172:175], v143 offset:16384
	ds_read_b128 v[176:179], v143 offset:17408
	ds_read_b128 v[180:183], v143 offset:18432
	ds_read_b128 v[184:187], v143 offset:19456
	ds_read_b128 v[188:191], v143 offset:20480
	ds_read_b128 v[192:195], v143 offset:21504
	ds_read_b128 v[196:199], v143 offset:22528
	ds_read_b128 v[200:203], v143 offset:23552
	global_load_lds_dwordx4 v96, s[44:45]
	s_add_i32 m0, s18, 0x2000
	s_add_u32 s18, s44, 0x40000
	s_addc_u32 s19, s45, 0
	s_add_i32 s35, s49, s14
	global_load_lds_dwordx4 v134, s[44:45]
	s_mov_b32 m0, s35
	s_nop 0
	global_load_lds_dwordx4 v96, s[18:19]
	s_add_i32 m0, s35, 0x2000
	s_nop 0
	global_load_lds_dwordx4 v134, s[18:19]
	s_waitcnt vmcnt(6)
	s_waitcnt lgkmcnt(0)
	s_barrier
	s_setprio 1
	s_waitcnt lgkmcnt(0)
	v_mfma_f32_16x16x32_bf16 v[60:63], v[136:139], v[172:175], 0
	v_mfma_f32_16x16x32_bf16 v[56:59], v[148:151], v[172:175], 0
	v_mfma_f32_16x16x32_bf16 v[44:47], v[136:139], v[180:183], 0
	v_mfma_f32_16x16x32_bf16 v[40:43], v[148:151], v[180:183], 0
	v_mfma_f32_16x16x32_bf16 v[28:31], v[136:139], v[188:191], 0
	v_mfma_f32_16x16x32_bf16 v[24:27], v[148:151], v[188:191], 0
	v_mfma_f32_16x16x32_bf16 v[12:15], v[136:139], v[196:199], 0
	v_mfma_f32_16x16x32_bf16 v[8:11], v[148:151], v[196:199], 0
	v_mfma_f32_16x16x32_bf16 v[60:63], v[144:147], v[176:179], v[60:63]
	v_mfma_f32_16x16x32_bf16 v[56:59], v[152:155], v[176:179], v[56:59]
	v_mfma_f32_16x16x32_bf16 v[44:47], v[144:147], v[184:187], v[44:47]
	v_mfma_f32_16x16x32_bf16 v[40:43], v[152:155], v[184:187], v[40:43]
	v_mfma_f32_16x16x32_bf16 v[28:31], v[144:147], v[192:195], v[28:31]
	v_mfma_f32_16x16x32_bf16 v[24:27], v[152:155], v[192:195], v[24:27]
	v_mfma_f32_16x16x32_bf16 v[12:15], v[144:147], v[200:203], v[12:15]
	v_mfma_f32_16x16x32_bf16 v[8:11], v[152:155], v[200:203], v[8:11]
	v_mfma_f32_16x16x32_bf16 v[52:55], v[156:159], v[172:175], 0
	v_mfma_f32_16x16x32_bf16 v[48:51], v[164:167], v[172:175], 0
	v_mfma_f32_16x16x32_bf16 v[36:39], v[156:159], v[180:183], 0
	v_mfma_f32_16x16x32_bf16 v[32:35], v[164:167], v[180:183], 0
	v_mfma_f32_16x16x32_bf16 v[20:23], v[156:159], v[188:191], 0
	v_mfma_f32_16x16x32_bf16 v[16:19], v[164:167], v[188:191], 0
	v_mfma_f32_16x16x32_bf16 v[4:7], v[156:159], v[196:199], 0
	v_mfma_f32_16x16x32_bf16 v[0:3], v[164:167], v[196:199], 0
	v_mfma_f32_16x16x32_bf16 v[52:55], v[160:163], v[176:179], v[52:55]
	v_mfma_f32_16x16x32_bf16 v[48:51], v[168:171], v[176:179], v[48:51]
	v_mfma_f32_16x16x32_bf16 v[36:39], v[160:163], v[184:187], v[36:39]
	v_mfma_f32_16x16x32_bf16 v[32:35], v[168:171], v[184:187], v[32:35]
	v_mfma_f32_16x16x32_bf16 v[20:23], v[160:163], v[192:195], v[20:23]
	v_mfma_f32_16x16x32_bf16 v[16:19], v[168:171], v[192:195], v[16:19]
	v_mfma_f32_16x16x32_bf16 v[4:7], v[160:163], v[200:203], v[4:7]
	v_mfma_f32_16x16x32_bf16 v[0:3], v[168:171], v[200:203], v[0:3]
	s_setprio 0
	s_barrier
	s_add_i32 s35, 0, 0x18000
	v_add_u32_e32 v140, s35, v142
	s_add_i32 s44, 0, 0x1c000
	ds_read_b128 v[136:139], v140
	ds_read_b128 v[144:147], v140 offset:1024
	ds_read_b128 v[148:151], v140 offset:2048
	ds_read_b128 v[152:155], v140 offset:3072
	v_add_u32_e32 v140, s44, v142
	ds_read_b128 v[156:159], v140
	ds_read_b128 v[160:163], v140 offset:1024
	ds_read_b128 v[164:167], v140 offset:2048
	ds_read_b128 v[168:171], v140 offset:3072
	s_mov_b32 m0, s67
	s_nop 0
	global_load_lds_dwordx4 v130, s[42:43]
	s_mov_b32 m0, s73
	s_nop 0
	global_load_lds_dwordx4 v132, s[42:43]
	s_add_u32 s18, s42, 0x40000
	s_addc_u32 s19, s43, 0
	s_mov_b32 m0, s76
	ds_read_b128 v[172:175], v143 offset:32768
	ds_read_b128 v[176:179], v143 offset:33792
	ds_read_b128 v[180:183], v143 offset:34816
	ds_read_b128 v[184:187], v143 offset:35840
	ds_read_b128 v[188:191], v143 offset:36864
	ds_read_b128 v[192:195], v143 offset:37888
	ds_read_b128 v[196:199], v143 offset:38912
	ds_read_b128 v[200:203], v143 offset:39936
	global_load_lds_dwordx4 v130, s[18:19]
	s_mov_b32 m0, s77
	s_nop 0
	global_load_lds_dwordx4 v132, s[18:19]
	s_waitcnt vmcnt(8)
	s_waitcnt lgkmcnt(0)
	s_barrier
	s_setprio 1
	s_waitcnt lgkmcnt(0)
	v_mfma_f32_16x16x32_bf16 v[126:129], v[136:139], v[172:175], v[126:129]
	v_mfma_f32_16x16x32_bf16 v[122:125], v[148:151], v[172:175], v[122:125]
	v_mfma_f32_16x16x32_bf16 v[110:113], v[136:139], v[180:183], v[110:113]
	v_mfma_f32_16x16x32_bf16 v[106:109], v[148:151], v[180:183], v[106:109]
	v_mfma_f32_16x16x32_bf16 v[92:95], v[136:139], v[188:191], v[92:95]
	v_mfma_f32_16x16x32_bf16 v[88:91], v[148:151], v[188:191], v[88:91]
	v_mfma_f32_16x16x32_bf16 v[76:79], v[136:139], v[196:199], v[76:79]
	v_mfma_f32_16x16x32_bf16 v[72:75], v[148:151], v[196:199], v[72:75]
	v_mfma_f32_16x16x32_bf16 v[126:129], v[144:147], v[176:179], v[126:129]
	v_mfma_f32_16x16x32_bf16 v[122:125], v[152:155], v[176:179], v[122:125]
	v_mfma_f32_16x16x32_bf16 v[110:113], v[144:147], v[184:187], v[110:113]
	v_mfma_f32_16x16x32_bf16 v[106:109], v[152:155], v[184:187], v[106:109]
	v_mfma_f32_16x16x32_bf16 v[92:95], v[144:147], v[192:195], v[92:95]
	v_mfma_f32_16x16x32_bf16 v[88:91], v[152:155], v[192:195], v[88:91]
	v_mfma_f32_16x16x32_bf16 v[76:79], v[144:147], v[200:203], v[76:79]
	v_mfma_f32_16x16x32_bf16 v[72:75], v[152:155], v[200:203], v[72:75]
	v_mfma_f32_16x16x32_bf16 v[118:121], v[156:159], v[172:175], v[118:121]
	v_mfma_f32_16x16x32_bf16 v[114:117], v[164:167], v[172:175], v[114:117]
	v_mfma_f32_16x16x32_bf16 v[102:105], v[156:159], v[180:183], v[102:105]
	v_mfma_f32_16x16x32_bf16 v[98:101], v[164:167], v[180:183], v[98:101]
	v_mfma_f32_16x16x32_bf16 v[84:87], v[156:159], v[188:191], v[84:87]
	v_mfma_f32_16x16x32_bf16 v[80:83], v[164:167], v[188:191], v[80:83]
	v_mfma_f32_16x16x32_bf16 v[68:71], v[156:159], v[196:199], v[68:71]
	v_mfma_f32_16x16x32_bf16 v[64:67], v[164:167], v[196:199], v[64:67]
	v_mfma_f32_16x16x32_bf16 v[118:121], v[160:163], v[176:179], v[118:121]
	v_mfma_f32_16x16x32_bf16 v[114:117], v[168:171], v[176:179], v[114:117]
	v_mfma_f32_16x16x32_bf16 v[102:105], v[160:163], v[184:187], v[102:105]
	v_mfma_f32_16x16x32_bf16 v[98:101], v[168:171], v[184:187], v[98:101]
	v_mfma_f32_16x16x32_bf16 v[84:87], v[160:163], v[192:195], v[84:87]
	v_mfma_f32_16x16x32_bf16 v[80:83], v[168:171], v[192:195], v[80:83]
	v_mfma_f32_16x16x32_bf16 v[68:71], v[160:163], v[200:203], v[68:71]
	v_mfma_f32_16x16x32_bf16 v[64:67], v[168:171], v[200:203], v[64:67]
	s_setprio 0
	s_barrier
	s_add_i32 s18, s35, s14
	s_mov_b32 m0, s18
	ds_read_b128 v[172:175], v143 offset:49152
	ds_read_b128 v[176:179], v143 offset:50176
	ds_read_b128 v[180:183], v143 offset:51200
	ds_read_b128 v[184:187], v143 offset:52224
	ds_read_b128 v[188:191], v143 offset:53248
	ds_read_b128 v[192:195], v143 offset:54272
	ds_read_b128 v[196:199], v143 offset:55296
	ds_read_b128 v[200:203], v143 offset:56320
	global_load_lds_dwordx4 v96, s[74:75]
	s_add_i32 m0, s18, 0x2000
	s_add_u32 s18, s74, 0x40000
	s_addc_u32 s19, s75, 0
	s_add_i32 s35, s44, s14
	global_load_lds_dwordx4 v134, s[74:75]
	s_mov_b32 m0, s35
	s_nop 0
	global_load_lds_dwordx4 v96, s[18:19]
	s_add_i32 m0, s35, 0x2000
	s_nop 0
	global_load_lds_dwordx4 v134, s[18:19]
	s_waitcnt vmcnt(6)
	s_waitcnt lgkmcnt(0)
	s_barrier
	s_setprio 1
	s_waitcnt lgkmcnt(0)
	v_mfma_f32_16x16x32_bf16 v[60:63], v[136:139], v[172:175], v[60:63]
	v_mfma_f32_16x16x32_bf16 v[56:59], v[148:151], v[172:175], v[56:59]
	v_mfma_f32_16x16x32_bf16 v[44:47], v[136:139], v[180:183], v[44:47]
	v_mfma_f32_16x16x32_bf16 v[40:43], v[148:151], v[180:183], v[40:43]
	v_mfma_f32_16x16x32_bf16 v[28:31], v[136:139], v[188:191], v[28:31]
	v_mfma_f32_16x16x32_bf16 v[24:27], v[148:151], v[188:191], v[24:27]
	v_mfma_f32_16x16x32_bf16 v[12:15], v[136:139], v[196:199], v[12:15]
	v_mfma_f32_16x16x32_bf16 v[8:11], v[148:151], v[196:199], v[8:11]
	v_mfma_f32_16x16x32_bf16 v[60:63], v[144:147], v[176:179], v[60:63]
	v_mfma_f32_16x16x32_bf16 v[56:59], v[152:155], v[176:179], v[56:59]
	v_mfma_f32_16x16x32_bf16 v[44:47], v[144:147], v[184:187], v[44:47]
	v_mfma_f32_16x16x32_bf16 v[40:43], v[152:155], v[184:187], v[40:43]
	v_mfma_f32_16x16x32_bf16 v[28:31], v[144:147], v[192:195], v[28:31]
	v_mfma_f32_16x16x32_bf16 v[24:27], v[152:155], v[192:195], v[24:27]
	v_mfma_f32_16x16x32_bf16 v[12:15], v[144:147], v[200:203], v[12:15]
	v_mfma_f32_16x16x32_bf16 v[8:11], v[152:155], v[200:203], v[8:11]
	v_mfma_f32_16x16x32_bf16 v[52:55], v[156:159], v[172:175], v[52:55]
	v_mfma_f32_16x16x32_bf16 v[48:51], v[164:167], v[172:175], v[48:51]
	v_mfma_f32_16x16x32_bf16 v[36:39], v[156:159], v[180:183], v[36:39]
	v_mfma_f32_16x16x32_bf16 v[32:35], v[164:167], v[180:183], v[32:35]
	v_mfma_f32_16x16x32_bf16 v[20:23], v[156:159], v[188:191], v[20:23]
	v_mfma_f32_16x16x32_bf16 v[16:19], v[164:167], v[188:191], v[16:19]
	v_mfma_f32_16x16x32_bf16 v[4:7], v[156:159], v[196:199], v[4:7]
	v_mfma_f32_16x16x32_bf16 v[0:3], v[164:167], v[196:199], v[0:3]
	v_mfma_f32_16x16x32_bf16 v[52:55], v[160:163], v[176:179], v[52:55]
	v_mfma_f32_16x16x32_bf16 v[48:51], v[168:171], v[176:179], v[48:51]
	v_mfma_f32_16x16x32_bf16 v[36:39], v[160:163], v[184:187], v[36:39]
	v_mfma_f32_16x16x32_bf16 v[32:35], v[168:171], v[184:187], v[32:35]
	v_mfma_f32_16x16x32_bf16 v[20:23], v[160:163], v[192:195], v[20:23]
	v_mfma_f32_16x16x32_bf16 v[16:19], v[168:171], v[192:195], v[16:19]
	v_mfma_f32_16x16x32_bf16 v[4:7], v[160:163], v[200:203], v[4:7]
	v_mfma_f32_16x16x32_bf16 v[0:3], v[168:171], v[200:203], v[0:3]
	s_setprio 0
	s_barrier
	s_add_i32 s89, s89, 2
	s_add_u32 s65, s65, 0x100
	s_addc_u32 s86, s86, 0
	s_add_u32 s87, s87, 0x100
	s_addc_u32 s88, s88, 0
	s_add_u32 s68, s68, 0x100
	s_addc_u32 s69, s69, 0
	s_cmp_gt_u32 s89, 13
	s_cbranch_scc0 .LBB0_122

.LBB0_432:
	s_ashr_i32 s87, s86, 31
	s_lshl_b64 s[18:19], s[86:87], 19
	s_add_u32 s88, s33, s18
	s_addc_u32 s89, s46, s19
	s_and_b64 s[18:19], s[6:7], exec
	s_cselect_b32 s9, s89, s11
	s_cselect_b32 s87, s88, s10
	s_ashr_i32 s85, s84, 31
	s_lshl_b64 s[18:19], s[84:85], 19
	s_add_u32 s90, s47, s18
	s_addc_u32 s91, s71, s19
	s_and_b64 s[18:19], s[6:7], exec
	s_cselect_b32 s85, s91, s39
	s_cselect_b32 vcc_lo, s90, s38
	s_add_u32 vcc_hi, s38, 0x100
	s_addc_u32 s94, s39, 0
	s_mov_b32 s92, -2
	s_add_u32 s18, s10, 0x80
	s_addc_u32 s19, s11, 0
	s_add_u32 s10, s10, 0x100
	s_addc_u32 s11, s11, 0
	s_cmp_eq_u32 s92, 12
	s_cselect_b32 s42, s87, s10
	s_cselect_b32 s43, s9, s11
	s_cselect_b32 s45, s85, s94
	s_cselect_b32 s44, vcc_lo, vcc_hi
	s_add_u32 s38, s42, 0x80
	s_addc_u32 s39, s43, 0
	s_add_u32 s68, s44, 0x80
	s_addc_u32 s69, s45, 0
	s_add_i32 s35, 0, 0x10000
	s_add_i32 s49, 0, 0x14000
	v_add_u32_e32 v96, s35, v199
	v_add_u32_e32 v166, s49, v199
	ds_read_b128 v[138:141], v96
	ds_read_b128 v[142:145], v96 offset:1024
	ds_read_b128 v[146:149], v96 offset:2048
	ds_read_b128 v[150:153], v96 offset:3072
	s_waitcnt lgkmcnt(0)
	ds_read_b128 v[154:157], v166
	ds_read_b128 v[158:161], v166 offset:1024
	ds_read_b128 v[162:165], v166 offset:2048
	ds_read_b128 v[166:169], v166 offset:3072
	s_mov_b32 m0, s29
	ds_read_b128 v[170:173], v200
	ds_read_b128 v[174:177], v200 offset:1024
	ds_read_b128 v[178:181], v200 offset:2048
	ds_read_b128 v[182:185], v200 offset:3072
	ds_read_b128 v[190:193], v200 offset:4096
	ds_read_b128 v[194:197], v200 offset:5120
	ds_read_b128 v[202:205], v200 offset:6144
	ds_read_b128 v[206:209], v200 offset:7168
	global_load_lds_dwordx4 v130, s[18:19]
	s_mov_b32 m0, s16
	s_nop 0
	global_load_lds_dwordx4 v134, s[18:19]
	s_add_u32 s18, s18, 0x40000
	s_addc_u32 s19, s19, 0
	s_add_i32 m0, s73, 0xc000
	s_nop 0
	global_load_lds_dwordx4 v130, s[18:19]
	s_add_i32 m0, s73, 0xe000
	s_nop 0
	global_load_lds_dwordx4 v134, s[18:19]
	s_waitcnt vmcnt(8)
	s_waitcnt lgkmcnt(0)
	s_barrier
	s_setprio 1
	s_waitcnt lgkmcnt(0)
	v_mfma_f32_16x16x32_bf16 v[126:129], v[138:141], v[170:173], 0
	v_mfma_f32_16x16x32_bf16 v[122:125], v[146:149], v[170:173], 0
	v_mfma_f32_16x16x32_bf16 v[118:121], v[138:141], v[178:181], 0
	v_mfma_f32_16x16x32_bf16 v[110:113], v[146:149], v[178:181], 0
	v_mfma_f32_16x16x32_bf16 v[102:105], v[138:141], v[190:193], 0
	v_mfma_f32_16x16x32_bf16 v[92:95], v[146:149], v[190:193], 0
	v_mfma_f32_16x16x32_bf16 v[84:87], v[138:141], v[202:205], 0
	v_mfma_f32_16x16x32_bf16 v[76:79], v[146:149], v[202:205], 0
	v_mfma_f32_16x16x32_bf16 v[126:129], v[142:145], v[174:177], v[126:129]
	v_mfma_f32_16x16x32_bf16 v[122:125], v[150:153], v[174:177], v[122:125]
	v_mfma_f32_16x16x32_bf16 v[118:121], v[142:145], v[182:185], v[118:121]
	v_mfma_f32_16x16x32_bf16 v[110:113], v[150:153], v[182:185], v[110:113]
	v_mfma_f32_16x16x32_bf16 v[102:105], v[142:145], v[194:197], v[102:105]
	v_mfma_f32_16x16x32_bf16 v[92:95], v[150:153], v[194:197], v[92:95]
	v_mfma_f32_16x16x32_bf16 v[84:87], v[142:145], v[206:209], v[84:87]
	v_mfma_f32_16x16x32_bf16 v[76:79], v[150:153], v[206:209], v[76:79]
	v_mfma_f32_16x16x32_bf16 v[114:117], v[154:157], v[170:173], 0
	v_mfma_f32_16x16x32_bf16 v[106:109], v[162:165], v[170:173], 0
	v_mfma_f32_16x16x32_bf16 v[98:101], v[154:157], v[178:181], 0
	v_mfma_f32_16x16x32_bf16 v[88:91], v[162:165], v[178:181], 0
	v_mfma_f32_16x16x32_bf16 v[80:83], v[154:157], v[190:193], 0
	v_mfma_f32_16x16x32_bf16 v[72:75], v[162:165], v[190:193], 0
	v_mfma_f32_16x16x32_bf16 v[68:71], v[154:157], v[202:205], 0
	v_mfma_f32_16x16x32_bf16 v[64:67], v[162:165], v[202:205], 0
	v_mfma_f32_16x16x32_bf16 v[114:117], v[158:161], v[174:177], v[114:117]
	v_mfma_f32_16x16x32_bf16 v[106:109], v[166:169], v[174:177], v[106:109]
	v_mfma_f32_16x16x32_bf16 v[98:101], v[158:161], v[182:185], v[98:101]
	v_mfma_f32_16x16x32_bf16 v[88:91], v[166:169], v[182:185], v[88:91]
	v_mfma_f32_16x16x32_bf16 v[80:83], v[158:161], v[194:197], v[80:83]
	v_mfma_f32_16x16x32_bf16 v[72:75], v[166:169], v[194:197], v[72:75]
	v_mfma_f32_16x16x32_bf16 v[68:71], v[158:161], v[206:209], v[68:71]
	v_mfma_f32_16x16x32_bf16 v[64:67], v[166:169], v[206:209], v[64:67]
	s_setprio 0
	s_barrier
	s_add_i32 s18, s35, s72
	s_mov_b32 m0, s18
	ds_read_b128 v[170:173], v200 offset:16384
	ds_read_b128 v[174:177], v200 offset:17408
	ds_read_b128 v[178:181], v200 offset:18432
	ds_read_b128 v[182:185], v200 offset:19456
	ds_read_b128 v[190:193], v200 offset:20480
	ds_read_b128 v[194:197], v200 offset:21504
	ds_read_b128 v[202:205], v200 offset:22528
	ds_read_b128 v[206:209], v200 offset:23552
	global_load_lds_dwordx4 v132, s[44:45]
	s_add_i32 m0, s18, 0x2000
	s_add_u32 s18, s44, 0x40000
	s_addc_u32 s19, s45, 0
	s_add_i32 s35, s49, s72
	global_load_lds_dwordx4 v136, s[44:45]
	s_mov_b32 m0, s35
	s_nop 0
	global_load_lds_dwordx4 v132, s[18:19]
	s_add_i32 m0, s35, 0x2000
	s_nop 0
	global_load_lds_dwordx4 v136, s[18:19]
	s_waitcnt vmcnt(6)
	s_waitcnt lgkmcnt(0)
	s_barrier
	s_setprio 1
	s_waitcnt lgkmcnt(0)
	v_mfma_f32_16x16x32_bf16 v[60:63], v[138:141], v[170:173], 0
	v_mfma_f32_16x16x32_bf16 v[56:59], v[146:149], v[170:173], 0
	v_mfma_f32_16x16x32_bf16 v[52:55], v[138:141], v[178:181], 0
	v_mfma_f32_16x16x32_bf16 v[44:47], v[146:149], v[178:181], 0
	v_mfma_f32_16x16x32_bf16 v[36:39], v[138:141], v[190:193], 0
	v_mfma_f32_16x16x32_bf16 v[28:31], v[146:149], v[190:193], 0
	v_mfma_f32_16x16x32_bf16 v[20:23], v[138:141], v[202:205], 0
	v_mfma_f32_16x16x32_bf16 v[12:15], v[146:149], v[202:205], 0
	v_mfma_f32_16x16x32_bf16 v[60:63], v[142:145], v[174:177], v[60:63]
	v_mfma_f32_16x16x32_bf16 v[56:59], v[150:153], v[174:177], v[56:59]
	v_mfma_f32_16x16x32_bf16 v[52:55], v[142:145], v[182:185], v[52:55]
	v_mfma_f32_16x16x32_bf16 v[44:47], v[150:153], v[182:185], v[44:47]
	v_mfma_f32_16x16x32_bf16 v[36:39], v[142:145], v[194:197], v[36:39]
	v_mfma_f32_16x16x32_bf16 v[28:31], v[150:153], v[194:197], v[28:31]
	v_mfma_f32_16x16x32_bf16 v[20:23], v[142:145], v[206:209], v[20:23]
	v_mfma_f32_16x16x32_bf16 v[12:15], v[150:153], v[206:209], v[12:15]
	v_mfma_f32_16x16x32_bf16 v[48:51], v[154:157], v[170:173], 0
	v_mfma_f32_16x16x32_bf16 v[40:43], v[162:165], v[170:173], 0
	v_mfma_f32_16x16x32_bf16 v[32:35], v[154:157], v[178:181], 0
	v_mfma_f32_16x16x32_bf16 v[24:27], v[162:165], v[178:181], 0
	v_mfma_f32_16x16x32_bf16 v[16:19], v[154:157], v[190:193], 0
	v_mfma_f32_16x16x32_bf16 v[8:11], v[162:165], v[190:193], 0
	v_mfma_f32_16x16x32_bf16 v[4:7], v[154:157], v[202:205], 0
	v_mfma_f32_16x16x32_bf16 v[0:3], v[162:165], v[202:205], 0
	v_mfma_f32_16x16x32_bf16 v[48:51], v[158:161], v[174:177], v[48:51]
	v_mfma_f32_16x16x32_bf16 v[40:43], v[166:169], v[174:177], v[40:43]
	v_mfma_f32_16x16x32_bf16 v[32:35], v[158:161], v[182:185], v[32:35]
	v_mfma_f32_16x16x32_bf16 v[24:27], v[166:169], v[182:185], v[24:27]
	v_mfma_f32_16x16x32_bf16 v[16:19], v[158:161], v[194:197], v[16:19]
	v_mfma_f32_16x16x32_bf16 v[8:11], v[166:169], v[194:197], v[8:11]
	v_mfma_f32_16x16x32_bf16 v[4:7], v[158:161], v[206:209], v[4:7]
	v_mfma_f32_16x16x32_bf16 v[0:3], v[166:169], v[206:209], v[0:3]
	s_setprio 0
	s_barrier
	s_add_i32 s35, 0, 0x18000
	v_add_u32_e32 v96, s35, v199
	s_add_i32 s44, 0, 0x1c000
	ds_read_b128 v[138:141], v96
	ds_read_b128 v[142:145], v96 offset:1024
	ds_read_b128 v[146:149], v96 offset:2048
	ds_read_b128 v[150:153], v96 offset:3072
	v_add_u32_e32 v96, s44, v199
	ds_read_b128 v[154:157], v96
	ds_read_b128 v[158:161], v96 offset:1024
	ds_read_b128 v[162:165], v96 offset:2048
	ds_read_b128 v[166:169], v96 offset:3072
	s_mov_b32 m0, s73
	s_nop 0
	global_load_lds_dwordx4 v130, s[42:43]
	s_mov_b32 m0, s74
	s_nop 0
	global_load_lds_dwordx4 v134, s[42:43]
	s_add_u32 s18, s42, 0x40000
	s_addc_u32 s19, s43, 0
	s_mov_b32 m0, s75
	ds_read_b128 v[170:173], v200 offset:32768
	ds_read_b128 v[174:177], v200 offset:33792
	ds_read_b128 v[178:181], v200 offset:34816
	ds_read_b128 v[182:185], v200 offset:35840
	ds_read_b128 v[190:193], v200 offset:36864
	ds_read_b128 v[194:197], v200 offset:37888
	ds_read_b128 v[202:205], v200 offset:38912
	ds_read_b128 v[206:209], v200 offset:39936
	global_load_lds_dwordx4 v130, s[18:19]
	s_mov_b32 m0, s83
	s_nop 0
	global_load_lds_dwordx4 v134, s[18:19]
	s_waitcnt vmcnt(8)
	s_waitcnt lgkmcnt(0)
	s_barrier
	s_setprio 1
	s_waitcnt lgkmcnt(0)
	v_mfma_f32_16x16x32_bf16 v[126:129], v[138:141], v[170:173], v[126:129]
	v_mfma_f32_16x16x32_bf16 v[122:125], v[146:149], v[170:173], v[122:125]
	v_mfma_f32_16x16x32_bf16 v[118:121], v[138:141], v[178:181], v[118:121]
	v_mfma_f32_16x16x32_bf16 v[110:113], v[146:149], v[178:181], v[110:113]
	v_mfma_f32_16x16x32_bf16 v[102:105], v[138:141], v[190:193], v[102:105]
	v_mfma_f32_16x16x32_bf16 v[92:95], v[146:149], v[190:193], v[92:95]
	v_mfma_f32_16x16x32_bf16 v[84:87], v[138:141], v[202:205], v[84:87]
	v_mfma_f32_16x16x32_bf16 v[76:79], v[146:149], v[202:205], v[76:79]
	v_mfma_f32_16x16x32_bf16 v[126:129], v[142:145], v[174:177], v[126:129]
	v_mfma_f32_16x16x32_bf16 v[122:125], v[150:153], v[174:177], v[122:125]
	v_mfma_f32_16x16x32_bf16 v[118:121], v[142:145], v[182:185], v[118:121]
	v_mfma_f32_16x16x32_bf16 v[110:113], v[150:153], v[182:185], v[110:113]
	v_mfma_f32_16x16x32_bf16 v[102:105], v[142:145], v[194:197], v[102:105]
	v_mfma_f32_16x16x32_bf16 v[92:95], v[150:153], v[194:197], v[92:95]
	v_mfma_f32_16x16x32_bf16 v[84:87], v[142:145], v[206:209], v[84:87]
	v_mfma_f32_16x16x32_bf16 v[76:79], v[150:153], v[206:209], v[76:79]
	v_mfma_f32_16x16x32_bf16 v[114:117], v[154:157], v[170:173], v[114:117]
	v_mfma_f32_16x16x32_bf16 v[106:109], v[162:165], v[170:173], v[106:109]
	v_mfma_f32_16x16x32_bf16 v[98:101], v[154:157], v[178:181], v[98:101]
	v_mfma_f32_16x16x32_bf16 v[88:91], v[162:165], v[178:181], v[88:91]
	v_mfma_f32_16x16x32_bf16 v[80:83], v[154:157], v[190:193], v[80:83]
	v_mfma_f32_16x16x32_bf16 v[72:75], v[162:165], v[190:193], v[72:75]
	v_mfma_f32_16x16x32_bf16 v[68:71], v[154:157], v[202:205], v[68:71]
	v_mfma_f32_16x16x32_bf16 v[64:67], v[162:165], v[202:205], v[64:67]
	v_mfma_f32_16x16x32_bf16 v[114:117], v[158:161], v[174:177], v[114:117]
	v_mfma_f32_16x16x32_bf16 v[106:109], v[166:169], v[174:177], v[106:109]
	v_mfma_f32_16x16x32_bf16 v[98:101], v[158:161], v[182:185], v[98:101]
	v_mfma_f32_16x16x32_bf16 v[88:91], v[166:169], v[182:185], v[88:91]
	v_mfma_f32_16x16x32_bf16 v[80:83], v[158:161], v[194:197], v[80:83]
	v_mfma_f32_16x16x32_bf16 v[72:75], v[166:169], v[194:197], v[72:75]
	v_mfma_f32_16x16x32_bf16 v[68:71], v[158:161], v[206:209], v[68:71]
	v_mfma_f32_16x16x32_bf16 v[64:67], v[166:169], v[206:209], v[64:67]
	s_setprio 0
	s_barrier
	s_add_i32 s18, s35, s72
	s_mov_b32 m0, s18
	ds_read_b128 v[170:173], v200 offset:49152
	ds_read_b128 v[174:177], v200 offset:50176
	ds_read_b128 v[178:181], v200 offset:51200
	ds_read_b128 v[182:185], v200 offset:52224
	ds_read_b128 v[190:193], v200 offset:53248
	ds_read_b128 v[194:197], v200 offset:54272
	ds_read_b128 v[202:205], v200 offset:55296
	ds_read_b128 v[206:209], v200 offset:56320
	global_load_lds_dwordx4 v132, s[68:69]
	s_add_i32 m0, s18, 0x2000
	s_add_u32 s18, s68, 0x40000
	s_addc_u32 s19, s69, 0
	s_add_i32 s35, s44, s72
	global_load_lds_dwordx4 v136, s[68:69]
	s_mov_b32 m0, s35
	s_nop 0
	global_load_lds_dwordx4 v132, s[18:19]
	s_add_i32 m0, s35, 0x2000
	s_nop 0
	global_load_lds_dwordx4 v136, s[18:19]
	s_waitcnt vmcnt(6)
	s_waitcnt lgkmcnt(0)
	s_barrier
	s_setprio 1
	s_waitcnt lgkmcnt(0)
	v_mfma_f32_16x16x32_bf16 v[60:63], v[138:141], v[170:173], v[60:63]
	v_mfma_f32_16x16x32_bf16 v[56:59], v[146:149], v[170:173], v[56:59]
	v_mfma_f32_16x16x32_bf16 v[52:55], v[138:141], v[178:181], v[52:55]
	v_mfma_f32_16x16x32_bf16 v[44:47], v[146:149], v[178:181], v[44:47]
	v_mfma_f32_16x16x32_bf16 v[36:39], v[138:141], v[190:193], v[36:39]
	v_mfma_f32_16x16x32_bf16 v[28:31], v[146:149], v[190:193], v[28:31]
	v_mfma_f32_16x16x32_bf16 v[20:23], v[138:141], v[202:205], v[20:23]
	v_mfma_f32_16x16x32_bf16 v[12:15], v[146:149], v[202:205], v[12:15]
	v_mfma_f32_16x16x32_bf16 v[60:63], v[142:145], v[174:177], v[60:63]
	v_mfma_f32_16x16x32_bf16 v[56:59], v[150:153], v[174:177], v[56:59]
	v_mfma_f32_16x16x32_bf16 v[52:55], v[142:145], v[182:185], v[52:55]
	v_mfma_f32_16x16x32_bf16 v[44:47], v[150:153], v[182:185], v[44:47]
	v_mfma_f32_16x16x32_bf16 v[36:39], v[142:145], v[194:197], v[36:39]
	v_mfma_f32_16x16x32_bf16 v[28:31], v[150:153], v[194:197], v[28:31]
	v_mfma_f32_16x16x32_bf16 v[20:23], v[142:145], v[206:209], v[20:23]
	v_mfma_f32_16x16x32_bf16 v[12:15], v[150:153], v[206:209], v[12:15]
	v_mfma_f32_16x16x32_bf16 v[48:51], v[154:157], v[170:173], v[48:51]
	v_mfma_f32_16x16x32_bf16 v[40:43], v[162:165], v[170:173], v[40:43]
	v_mfma_f32_16x16x32_bf16 v[32:35], v[154:157], v[178:181], v[32:35]
	v_mfma_f32_16x16x32_bf16 v[24:27], v[162:165], v[178:181], v[24:27]
	v_mfma_f32_16x16x32_bf16 v[16:19], v[154:157], v[190:193], v[16:19]
	v_mfma_f32_16x16x32_bf16 v[8:11], v[162:165], v[190:193], v[8:11]
	v_mfma_f32_16x16x32_bf16 v[4:7], v[154:157], v[202:205], v[4:7]
	v_mfma_f32_16x16x32_bf16 v[0:3], v[162:165], v[202:205], v[0:3]
	v_mfma_f32_16x16x32_bf16 v[48:51], v[158:161], v[174:177], v[48:51]
	v_mfma_f32_16x16x32_bf16 v[40:43], v[166:169], v[174:177], v[40:43]
	v_mfma_f32_16x16x32_bf16 v[32:35], v[158:161], v[182:185], v[32:35]
	v_mfma_f32_16x16x32_bf16 v[24:27], v[166:169], v[182:185], v[24:27]
	v_mfma_f32_16x16x32_bf16 v[16:19], v[158:161], v[194:197], v[16:19]
	v_mfma_f32_16x16x32_bf16 v[8:11], v[166:169], v[194:197], v[8:11]
	v_mfma_f32_16x16x32_bf16 v[4:7], v[158:161], v[206:209], v[4:7]
	v_mfma_f32_16x16x32_bf16 v[0:3], v[166:169], v[206:209], v[0:3]
	s_setprio 0
	s_barrier
	s_add_i32 s92, s92, 2
	s_add_u32 vcc_hi, vcc_hi, 0x100
	s_addc_u32 s94, s94, 0
	s_cmp_gt_u32 s92, 13
	s_cbranch_scc0 .LBB0_433

.LBB0_702:
	s_add_u32 s81, s60, 0x100
	s_addc_u32 s82, s61, 0
	s_add_u32 s83, s38, 0x100
	s_addc_u32 s84, s39, 0
	s_add_u32 s60, s60, 0x80
	s_addc_u32 s61, s61, 0
	s_mov_b32 s85, -2
	s_cmp_eq_u32 s85, 40
	s_cselect_b32 s42, s8, s81
	s_cselect_b32 s43, s9, s82
	s_cselect_b32 s45, s59, s84
	s_cselect_b32 s44, s58, s83
	s_add_u32 s38, s42, 0x80
	s_addc_u32 s39, s43, 0
	s_add_u32 s62, s44, 0x80
	s_addc_u32 s63, s45, 0
	s_add_i32 s35, 0, 0x10000
	s_mov_b64 s[18:19], s[60:61]
	v_add_u32_e32 v140, s35, v142
	s_add_i32 s49, 0, 0x14000
	ds_read_b128 v[136:139], v140
	ds_read_b128 v[144:147], v140 offset:1024
	ds_read_b128 v[148:151], v140 offset:2048
	ds_read_b128 v[152:155], v140 offset:3072
	v_add_u32_e32 v140, s49, v142
	ds_read_b128 v[156:159], v140
	ds_read_b128 v[160:163], v140 offset:1024
	ds_read_b128 v[164:167], v140 offset:2048
	ds_read_b128 v[168:171], v140 offset:3072
	s_mov_b32 m0, s74
	ds_read_b128 v[172:175], v143
	ds_read_b128 v[176:179], v143 offset:1024
	ds_read_b128 v[180:183], v143 offset:2048
	ds_read_b128 v[190:193], v143 offset:3072
	ds_read_b128 v[194:197], v143 offset:4096
	ds_read_b128 v[198:201], v143 offset:5120
	ds_read_b128 v[202:205], v143 offset:6144
	ds_read_b128 v[206:209], v143 offset:7168
	global_load_lds_dwordx4 v130, s[18:19]
	s_mov_b32 m0, s75
	s_nop 0
	global_load_lds_dwordx4 v132, s[18:19]
	s_add_u32 s18, s18, 0xb0000
	s_addc_u32 s19, s19, 0
	s_add_i32 m0, s66, 0xc000
	s_nop 0
	global_load_lds_dwordx4 v130, s[18:19]
	s_add_i32 m0, s66, 0xe000
	s_nop 0
	global_load_lds_dwordx4 v132, s[18:19]
	s_waitcnt vmcnt(8)
	s_waitcnt lgkmcnt(0)
	s_barrier
	s_setprio 1
	s_waitcnt lgkmcnt(0)
	v_mfma_f32_16x16x32_bf16 v[126:129], v[136:139], v[172:175], 0
	v_mfma_f32_16x16x32_bf16 v[122:125], v[148:151], v[172:175], 0
	v_mfma_f32_16x16x32_bf16 v[110:113], v[136:139], v[180:183], 0
	v_mfma_f32_16x16x32_bf16 v[106:109], v[148:151], v[180:183], 0
	v_mfma_f32_16x16x32_bf16 v[92:95], v[136:139], v[194:197], 0
	v_mfma_f32_16x16x32_bf16 v[88:91], v[148:151], v[194:197], 0
	v_mfma_f32_16x16x32_bf16 v[76:79], v[136:139], v[202:205], 0
	v_mfma_f32_16x16x32_bf16 v[72:75], v[148:151], v[202:205], 0
	v_mfma_f32_16x16x32_bf16 v[126:129], v[144:147], v[176:179], v[126:129]
	v_mfma_f32_16x16x32_bf16 v[122:125], v[152:155], v[176:179], v[122:125]
	v_mfma_f32_16x16x32_bf16 v[110:113], v[144:147], v[190:193], v[110:113]
	v_mfma_f32_16x16x32_bf16 v[106:109], v[152:155], v[190:193], v[106:109]
	v_mfma_f32_16x16x32_bf16 v[92:95], v[144:147], v[198:201], v[92:95]
	v_mfma_f32_16x16x32_bf16 v[88:91], v[152:155], v[198:201], v[88:91]
	v_mfma_f32_16x16x32_bf16 v[76:79], v[144:147], v[206:209], v[76:79]
	v_mfma_f32_16x16x32_bf16 v[72:75], v[152:155], v[206:209], v[72:75]
	v_mfma_f32_16x16x32_bf16 v[118:121], v[156:159], v[172:175], 0
	v_mfma_f32_16x16x32_bf16 v[114:117], v[164:167], v[172:175], 0
	v_mfma_f32_16x16x32_bf16 v[102:105], v[156:159], v[180:183], 0
	v_mfma_f32_16x16x32_bf16 v[98:101], v[164:167], v[180:183], 0
	v_mfma_f32_16x16x32_bf16 v[84:87], v[156:159], v[194:197], 0
	v_mfma_f32_16x16x32_bf16 v[80:83], v[164:167], v[194:197], 0
	v_mfma_f32_16x16x32_bf16 v[68:71], v[156:159], v[202:205], 0
	v_mfma_f32_16x16x32_bf16 v[64:67], v[164:167], v[202:205], 0
	v_mfma_f32_16x16x32_bf16 v[118:121], v[160:163], v[176:179], v[118:121]
	v_mfma_f32_16x16x32_bf16 v[114:117], v[168:171], v[176:179], v[114:117]
	v_mfma_f32_16x16x32_bf16 v[102:105], v[160:163], v[190:193], v[102:105]
	v_mfma_f32_16x16x32_bf16 v[98:101], v[168:171], v[190:193], v[98:101]
	v_mfma_f32_16x16x32_bf16 v[84:87], v[160:163], v[198:201], v[84:87]
	v_mfma_f32_16x16x32_bf16 v[80:83], v[168:171], v[198:201], v[80:83]
	v_mfma_f32_16x16x32_bf16 v[68:71], v[160:163], v[206:209], v[68:71]
	v_mfma_f32_16x16x32_bf16 v[64:67], v[168:171], v[206:209], v[64:67]
	s_setprio 0
	s_barrier
	s_add_i32 s18, s35, s14
	s_mov_b32 m0, s18
	ds_read_b128 v[172:175], v143 offset:16384
	ds_read_b128 v[176:179], v143 offset:17408
	ds_read_b128 v[180:183], v143 offset:18432
	ds_read_b128 v[190:193], v143 offset:19456
	ds_read_b128 v[194:197], v143 offset:20480
	ds_read_b128 v[198:201], v143 offset:21504
	ds_read_b128 v[202:205], v143 offset:22528
	ds_read_b128 v[206:209], v143 offset:23552
	global_load_lds_dwordx4 v96, s[44:45]
	s_add_i32 m0, s18, 0x2000
	s_add_u32 s18, s44, 0xb0000
	s_addc_u32 s19, s45, 0
	s_add_i32 s35, s49, s14
	global_load_lds_dwordx4 v134, s[44:45]
	s_mov_b32 m0, s35
	s_nop 0
	global_load_lds_dwordx4 v96, s[18:19]
	s_add_i32 m0, s35, 0x2000
	s_nop 0
	global_load_lds_dwordx4 v134, s[18:19]
	s_waitcnt vmcnt(6)
	s_waitcnt lgkmcnt(0)
	s_barrier
	s_setprio 1
	s_waitcnt lgkmcnt(0)
	v_mfma_f32_16x16x32_bf16 v[60:63], v[136:139], v[172:175], 0
	v_mfma_f32_16x16x32_bf16 v[56:59], v[148:151], v[172:175], 0
	v_mfma_f32_16x16x32_bf16 v[44:47], v[136:139], v[180:183], 0
	v_mfma_f32_16x16x32_bf16 v[40:43], v[148:151], v[180:183], 0
	v_mfma_f32_16x16x32_bf16 v[28:31], v[136:139], v[194:197], 0
	v_mfma_f32_16x16x32_bf16 v[24:27], v[148:151], v[194:197], 0
	v_mfma_f32_16x16x32_bf16 v[12:15], v[136:139], v[202:205], 0
	v_mfma_f32_16x16x32_bf16 v[8:11], v[148:151], v[202:205], 0
	v_mfma_f32_16x16x32_bf16 v[60:63], v[144:147], v[176:179], v[60:63]
	v_mfma_f32_16x16x32_bf16 v[56:59], v[152:155], v[176:179], v[56:59]
	v_mfma_f32_16x16x32_bf16 v[44:47], v[144:147], v[190:193], v[44:47]
	v_mfma_f32_16x16x32_bf16 v[40:43], v[152:155], v[190:193], v[40:43]
	v_mfma_f32_16x16x32_bf16 v[28:31], v[144:147], v[198:201], v[28:31]
	v_mfma_f32_16x16x32_bf16 v[24:27], v[152:155], v[198:201], v[24:27]
	v_mfma_f32_16x16x32_bf16 v[12:15], v[144:147], v[206:209], v[12:15]
	v_mfma_f32_16x16x32_bf16 v[8:11], v[152:155], v[206:209], v[8:11]
	v_mfma_f32_16x16x32_bf16 v[52:55], v[156:159], v[172:175], 0
	v_mfma_f32_16x16x32_bf16 v[48:51], v[164:167], v[172:175], 0
	v_mfma_f32_16x16x32_bf16 v[36:39], v[156:159], v[180:183], 0
	v_mfma_f32_16x16x32_bf16 v[32:35], v[164:167], v[180:183], 0
	v_mfma_f32_16x16x32_bf16 v[20:23], v[156:159], v[194:197], 0
	v_mfma_f32_16x16x32_bf16 v[16:19], v[164:167], v[194:197], 0
	v_mfma_f32_16x16x32_bf16 v[4:7], v[156:159], v[202:205], 0
	v_mfma_f32_16x16x32_bf16 v[0:3], v[164:167], v[202:205], 0
	v_mfma_f32_16x16x32_bf16 v[52:55], v[160:163], v[176:179], v[52:55]
	v_mfma_f32_16x16x32_bf16 v[48:51], v[168:171], v[176:179], v[48:51]
	v_mfma_f32_16x16x32_bf16 v[36:39], v[160:163], v[190:193], v[36:39]
	v_mfma_f32_16x16x32_bf16 v[32:35], v[168:171], v[190:193], v[32:35]
	v_mfma_f32_16x16x32_bf16 v[20:23], v[160:163], v[198:201], v[20:23]
	v_mfma_f32_16x16x32_bf16 v[16:19], v[168:171], v[198:201], v[16:19]
	v_mfma_f32_16x16x32_bf16 v[4:7], v[160:163], v[206:209], v[4:7]
	v_mfma_f32_16x16x32_bf16 v[0:3], v[168:171], v[206:209], v[0:3]
	s_setprio 0
	s_barrier
	s_add_i32 s35, 0, 0x18000
	v_add_u32_e32 v140, s35, v142
	s_add_i32 s44, 0, 0x1c000
	ds_read_b128 v[136:139], v140
	ds_read_b128 v[144:147], v140 offset:1024
	ds_read_b128 v[148:151], v140 offset:2048
	ds_read_b128 v[152:155], v140 offset:3072
	v_add_u32_e32 v140, s44, v142
	ds_read_b128 v[156:159], v140
	ds_read_b128 v[160:163], v140 offset:1024
	ds_read_b128 v[164:167], v140 offset:2048
	ds_read_b128 v[168:171], v140 offset:3072
	s_mov_b32 m0, s66
	s_nop 0
	global_load_lds_dwordx4 v130, s[42:43]
	s_mov_b32 m0, s67
	s_nop 0
	global_load_lds_dwordx4 v132, s[42:43]
	s_add_u32 s18, s42, 0xb0000
	s_addc_u32 s19, s43, 0
	s_mov_b32 m0, s68
	ds_read_b128 v[172:175], v143 offset:32768
	ds_read_b128 v[176:179], v143 offset:33792
	ds_read_b128 v[180:183], v143 offset:34816
	ds_read_b128 v[190:193], v143 offset:35840
	ds_read_b128 v[194:197], v143 offset:36864
	ds_read_b128 v[198:201], v143 offset:37888
	ds_read_b128 v[202:205], v143 offset:38912
	ds_read_b128 v[206:209], v143 offset:39936
	global_load_lds_dwordx4 v130, s[18:19]
	s_mov_b32 m0, s69
	s_nop 0
	global_load_lds_dwordx4 v132, s[18:19]
	s_waitcnt vmcnt(8)
	s_waitcnt lgkmcnt(0)
	s_barrier
	s_setprio 1
	s_waitcnt lgkmcnt(0)
	v_mfma_f32_16x16x32_bf16 v[126:129], v[136:139], v[172:175], v[126:129]
	v_mfma_f32_16x16x32_bf16 v[122:125], v[148:151], v[172:175], v[122:125]
	v_mfma_f32_16x16x32_bf16 v[110:113], v[136:139], v[180:183], v[110:113]
	v_mfma_f32_16x16x32_bf16 v[106:109], v[148:151], v[180:183], v[106:109]
	v_mfma_f32_16x16x32_bf16 v[92:95], v[136:139], v[194:197], v[92:95]
	v_mfma_f32_16x16x32_bf16 v[88:91], v[148:151], v[194:197], v[88:91]
	v_mfma_f32_16x16x32_bf16 v[76:79], v[136:139], v[202:205], v[76:79]
	v_mfma_f32_16x16x32_bf16 v[72:75], v[148:151], v[202:205], v[72:75]
	v_mfma_f32_16x16x32_bf16 v[126:129], v[144:147], v[176:179], v[126:129]
	v_mfma_f32_16x16x32_bf16 v[122:125], v[152:155], v[176:179], v[122:125]
	v_mfma_f32_16x16x32_bf16 v[110:113], v[144:147], v[190:193], v[110:113]
	v_mfma_f32_16x16x32_bf16 v[106:109], v[152:155], v[190:193], v[106:109]
	v_mfma_f32_16x16x32_bf16 v[92:95], v[144:147], v[198:201], v[92:95]
	v_mfma_f32_16x16x32_bf16 v[88:91], v[152:155], v[198:201], v[88:91]
	v_mfma_f32_16x16x32_bf16 v[76:79], v[144:147], v[206:209], v[76:79]
	v_mfma_f32_16x16x32_bf16 v[72:75], v[152:155], v[206:209], v[72:75]
	v_mfma_f32_16x16x32_bf16 v[118:121], v[156:159], v[172:175], v[118:121]
	v_mfma_f32_16x16x32_bf16 v[114:117], v[164:167], v[172:175], v[114:117]
	v_mfma_f32_16x16x32_bf16 v[102:105], v[156:159], v[180:183], v[102:105]
	v_mfma_f32_16x16x32_bf16 v[98:101], v[164:167], v[180:183], v[98:101]
	v_mfma_f32_16x16x32_bf16 v[84:87], v[156:159], v[194:197], v[84:87]
	v_mfma_f32_16x16x32_bf16 v[80:83], v[164:167], v[194:197], v[80:83]
	v_mfma_f32_16x16x32_bf16 v[68:71], v[156:159], v[202:205], v[68:71]
	v_mfma_f32_16x16x32_bf16 v[64:67], v[164:167], v[202:205], v[64:67]
	v_mfma_f32_16x16x32_bf16 v[118:121], v[160:163], v[176:179], v[118:121]
	v_mfma_f32_16x16x32_bf16 v[114:117], v[168:171], v[176:179], v[114:117]
	v_mfma_f32_16x16x32_bf16 v[102:105], v[160:163], v[190:193], v[102:105]
	v_mfma_f32_16x16x32_bf16 v[98:101], v[168:171], v[190:193], v[98:101]
	v_mfma_f32_16x16x32_bf16 v[84:87], v[160:163], v[198:201], v[84:87]
	v_mfma_f32_16x16x32_bf16 v[80:83], v[168:171], v[198:201], v[80:83]
	v_mfma_f32_16x16x32_bf16 v[68:71], v[160:163], v[206:209], v[68:71]
	v_mfma_f32_16x16x32_bf16 v[64:67], v[168:171], v[206:209], v[64:67]
	s_setprio 0
	s_barrier
	s_add_i32 s18, s35, s14
	s_mov_b32 m0, s18
	ds_read_b128 v[172:175], v143 offset:49152
	ds_read_b128 v[176:179], v143 offset:50176
	ds_read_b128 v[180:183], v143 offset:51200
	ds_read_b128 v[190:193], v143 offset:52224
	ds_read_b128 v[194:197], v143 offset:53248
	ds_read_b128 v[198:201], v143 offset:54272
	ds_read_b128 v[202:205], v143 offset:55296
	ds_read_b128 v[206:209], v143 offset:56320
	global_load_lds_dwordx4 v96, s[62:63]
	s_add_i32 m0, s18, 0x2000
	s_add_u32 s18, s62, 0xb0000
	s_addc_u32 s19, s63, 0
	s_add_i32 s35, s44, s14
	global_load_lds_dwordx4 v134, s[62:63]
	s_mov_b32 m0, s35
	s_nop 0
	global_load_lds_dwordx4 v96, s[18:19]
	s_add_i32 m0, s35, 0x2000
	s_nop 0
	global_load_lds_dwordx4 v134, s[18:19]
	s_waitcnt vmcnt(6)
	s_waitcnt lgkmcnt(0)
	s_barrier
	s_setprio 1
	s_waitcnt lgkmcnt(0)
	v_mfma_f32_16x16x32_bf16 v[60:63], v[136:139], v[172:175], v[60:63]
	v_mfma_f32_16x16x32_bf16 v[56:59], v[148:151], v[172:175], v[56:59]
	v_mfma_f32_16x16x32_bf16 v[44:47], v[136:139], v[180:183], v[44:47]
	v_mfma_f32_16x16x32_bf16 v[40:43], v[148:151], v[180:183], v[40:43]
	v_mfma_f32_16x16x32_bf16 v[28:31], v[136:139], v[194:197], v[28:31]
	v_mfma_f32_16x16x32_bf16 v[24:27], v[148:151], v[194:197], v[24:27]
	v_mfma_f32_16x16x32_bf16 v[12:15], v[136:139], v[202:205], v[12:15]
	v_mfma_f32_16x16x32_bf16 v[8:11], v[148:151], v[202:205], v[8:11]
	v_mfma_f32_16x16x32_bf16 v[60:63], v[144:147], v[176:179], v[60:63]
	v_mfma_f32_16x16x32_bf16 v[56:59], v[152:155], v[176:179], v[56:59]
	v_mfma_f32_16x16x32_bf16 v[44:47], v[144:147], v[190:193], v[44:47]
	v_mfma_f32_16x16x32_bf16 v[40:43], v[152:155], v[190:193], v[40:43]
	v_mfma_f32_16x16x32_bf16 v[28:31], v[144:147], v[198:201], v[28:31]
	v_mfma_f32_16x16x32_bf16 v[24:27], v[152:155], v[198:201], v[24:27]
	v_mfma_f32_16x16x32_bf16 v[12:15], v[144:147], v[206:209], v[12:15]
	v_mfma_f32_16x16x32_bf16 v[8:11], v[152:155], v[206:209], v[8:11]
	v_mfma_f32_16x16x32_bf16 v[52:55], v[156:159], v[172:175], v[52:55]
	v_mfma_f32_16x16x32_bf16 v[48:51], v[164:167], v[172:175], v[48:51]
	v_mfma_f32_16x16x32_bf16 v[36:39], v[156:159], v[180:183], v[36:39]
	v_mfma_f32_16x16x32_bf16 v[32:35], v[164:167], v[180:183], v[32:35]
	v_mfma_f32_16x16x32_bf16 v[20:23], v[156:159], v[194:197], v[20:23]
	v_mfma_f32_16x16x32_bf16 v[16:19], v[164:167], v[194:197], v[16:19]
	v_mfma_f32_16x16x32_bf16 v[4:7], v[156:159], v[202:205], v[4:7]
	v_mfma_f32_16x16x32_bf16 v[0:3], v[164:167], v[202:205], v[0:3]
	v_mfma_f32_16x16x32_bf16 v[52:55], v[160:163], v[176:179], v[52:55]
	v_mfma_f32_16x16x32_bf16 v[48:51], v[168:171], v[176:179], v[48:51]
	v_mfma_f32_16x16x32_bf16 v[36:39], v[160:163], v[190:193], v[36:39]
	v_mfma_f32_16x16x32_bf16 v[32:35], v[168:171], v[190:193], v[32:35]
	v_mfma_f32_16x16x32_bf16 v[20:23], v[160:163], v[198:201], v[20:23]
	v_mfma_f32_16x16x32_bf16 v[16:19], v[168:171], v[198:201], v[16:19]
	v_mfma_f32_16x16x32_bf16 v[4:7], v[160:163], v[206:209], v[4:7]
	v_mfma_f32_16x16x32_bf16 v[0:3], v[168:171], v[206:209], v[0:3]
	s_setprio 0
	s_barrier
	s_add_i32 s85, s85, 2
	s_add_u32 s81, s81, 0x100
	s_addc_u32 s82, s82, 0
	s_add_u32 s83, s83, 0x100
	s_addc_u32 s84, s84, 0
	s_add_u32 s60, s60, 0x100
	s_addc_u32 s61, s61, 0
	s_cmp_gt_u32 s85, 41
	s_cbranch_scc0 .LBB0_703
